# strategy 4: O3 phase runs waves 4-7 at static priority 1, per-cluster s_setprio flips neutralised (on v6)
# speedup vs baseline: 1.0038x; 1.0038x over previous
; #define LAS __attribute__((address_space(3)))
; #define MASKW ((unsigned*)WSP(WS_B + B_MASKW))
; template <int DQK, int DV, int MODE, bool QNORM, int SK, int NQ> ...
;     ...
;     int goff[NLD]; bool isk[NLD]; int gstep[NLD]; int ldst[NLD]; bool act[NLD];
; #pragma unroll
;     for (int i = 0; i < NLD; ++i) {
;         const int c = tid + i * 512; act[i] = c < NCH;
;         isk[i] = c < KCH;
;         if (c < KCH) { const int row = c / KCPR, ch = c % KCPR; goff[i] = row * k_pitch + ch * 8; gstep[i] = SK * k_pitch; ldst[i] = row * KP + ch * 16; }
;         else { const int c2 = c - KCH, row = c2 / VCPR, ch = c2 % VCPR; goff[i] = (row < DV ? row : 0) * vt_pitch + ch * 8; gstep[i] = SK; ldst[i] = KBYTES + row * VP + ch * 16; }
;     }
;     constexpr bool PF2 = (NQ == 1 && DQK <= 96);
;     u32x4 stg[NLD], stg2[NLD];
;     const int nstage = (nst + NSUB - 1) / NSUB;
; #pragma unroll
;     for (int i = 0; i < NLD; ++i) if (act[i]) stg2[i] = *(const u32x4*)((isk[i] ? Kp : Vt) + goff[i]);
;     if (PF2 && 1 < nstage) {
; #pragma unroll
;         for (int i = 0; i < NLD; ++i) if (act[i]) stg[i] = *(const u32x4*)((isk[i] ? Kp : Vt) + goff[i] + gstep[i]);
;     }
; #pragma unroll
;     for (int i = 0; i < NLD; ++i) if (act[i]) *(LAS u32x4*)(lds + ldst[i]) = stg2[i];
;     unsigned wcur0 = 0xffffffffu, wcur1 = 0xffffffffu;
;     const unsigned* mrow = (MODE == 1) ? (mw + (size_t)r32 * 64) : nullptr;
;     if (MODE == 1) { wcur0 = mrow[0]; wcur1 = (NSUB > 1 && 1 < nst) ? mrow[1] : 0u; }
;     __syncthreads();
; __global__ void __launch_bounds__(512, 2) mega_fwd(KArgs a) {
;     ...
;             for (int ub = blockIdx.x; ub < 512; ub += GRID_BLOCKS) {
;                 const int pass = ub >> 8, idx = ub & 255, b = idx & 7, i = idx >> 3;
;                 const int qt = pass ? i : 63 - i, q0 = qt * 32, h = wave * 2;
;                 f32x16 o[2][2]; float mm[2], ll[2];
;                 attn_block<64, 64, 1, false, 64, 2>(lds, QSP + ((size_t)(b * S_ + q0) * 16 + h) * 64, 1024, 64, KSP + (size_t)b * S_ * 64, 64, VTSP + (size_t)b * 64 * 2048, 2048,
;                                       qt + 1, qt + 1, q0, MASKW + (size_t)(b * S_ + q0) * 64, 0.f, o, mm, ll, tid);
.LBB0_3876:
	s_or_b64 exec, exec, s[0:1]
	v_readlane_b32 s2, v252, 8
	s_mov_b64 s[0:1], s[88:89]
	v_mov_b32_e32 v1, v220
	v_readlane_b32 s3, v252, 9
	s_waitcnt lgkmcnt(0)
	s_barrier
	v_readfirstlane_b32 vcc_lo, v220
	s_nop 1
	s_bitcmp1_b32 vcc_lo, 8
	s_cbranch_scc0 .Lmy_prio_skip_9
	s_setprio 1
.Lmy_prio_skip_9:
	s_andn2_b64 vcc, exec, s[2:3]
	v_readfirstlane_b32 s2, v1
	s_cbranch_vccnz .LBB0_3913
	s_load_dwordx2 s[0:1], s[0:1], 0x100
	s_ashr_i32 s8, s2, 5
	s_and_b32 s6, s8, -2
	s_ashr_i32 s7, s6, 31
	s_lshl_b64 s[2:3], s[6:7], 7
	v_and_b32_e32 v202, 31, v1
	s_waitcnt lgkmcnt(0)
	s_add_u32 s2, s0, s2
	v_bfe_u32 v8, v1, 5, 1
	s_addc_u32 s3, s1, s3
	v_lshlrev_b32_e32 v2, 11, v202
	v_mov_b32_e32 v3, v0
	v_lshl_add_u64 v[2:3], s[2:3], 0, v[2:3]
	v_lshlrev_b32_e32 v170, 4, v8
	v_mov_b32_e32 v171, v0
	v_lshl_add_u64 v[2:3], v[2:3], 0, v[170:171]
	s_mov_b64 s[2:3], 0xe400000
	v_lshl_add_u64 v[172:173], v[2:3], 0, s[2:3]
	v_and_b32_e32 v2, 7, v1
	v_mov_b32_e32 v4, 0x2400
	v_lshrrev_b32_e32 v6, 3, v1
	s_movk_i32 s7, 0x200
	v_lshlrev_b32_e32 v3, 3, v2
	v_lshl_or_b32 v2, v2, 4, v4
	v_lshlrev_b32_e32 v4, 11, v6
	v_subrev_co_u32_e32 v5, vcc, s7, v1
	s_movk_i32 s9, 0x90
	s_nop 0
	v_cndmask_b32_e32 v7, 0, v4, vcc
	v_lshrrev_b32_e32 v4, 3, v5
	v_lshlrev_b32_e32 v9, 11, v4
	v_cmp_gt_u32_e32 vcc, s7, v5
	v_or_b32_e32 v11, v7, v3
	v_mov_b32_e32 v7, v0
	v_cndmask_b32_e32 v5, 0, v9, vcc
	v_or_b32_e32 v9, v5, v3
	v_mad_u64_u32 v[4:5], s[2:3], v4, s9, v[2:3]
	v_mad_u64_u32 v[2:3], s[2:3], v6, s9, v[2:3]
	v_add_u32_e32 v3, 0x200, v1
	v_ashrrev_i32_e32 v6, 31, v3
	v_lshrrev_b32_e32 v6, 29, v6
	v_add_u32_e32 v6, v3, v6
	v_lshrrev_b32_e32 v6, 3, v6
	v_lshlrev_b32_e32 v12, 3, v3
	v_add_lshl_u32 v3, v6, v3, 4
	v_lshlrev_b32_e32 v6, 8, v202
	v_lshl_add_u64 v[6:7], s[0:1], 0, v[6:7]
	s_mov_b64 s[2:3], 0x11b00000
	v_lshl_add_u64 v[174:175], v[6:7], 0, s[2:3]
	v_lshlrev_b32_e32 v8, 2, v8
	s_movk_i32 s2, 0x100
	v_lshlrev_b32_e64 v207, v8, s2
	s_movk_i32 s2, 0x800
	v_lshlrev_b32_e64 v210, v8, s2
	s_mov_b32 s2, 0x10000
	v_lshlrev_b32_e64 v211, v8, s2
	s_mov_b32 s2, 0x20000
	v_lshlrev_b32_e64 v212, v8, s2
	s_mov_b32 s2, 0x40000
	v_lshlrev_b32_e64 v213, v8, s2
	s_mov_b32 s2, 0x80000
	v_lshlrev_b32_e64 v214, v8, s2
	s_mov_b32 s2, 0x1000000
	v_lshlrev_b32_e64 v215, v8, s2
	s_brev_b32 s2, 64
	v_lshlrev_b32_e64 v216, v8, s2
	s_brev_b32 s2, 32
	v_lshlrev_b32_e64 v217, v8, s2
	s_brev_b32 s2, 16
	v_lshlrev_b32_e64 v218, v8, s2
	s_add_u32 s2, s0, 0x8c00000
	s_addc_u32 s3, s1, 0
	s_lshl_b32 s72, s6, 6
	s_lshl_b32 s6, s8, 6
	s_or_b32 s74, s6, 64
	s_ashr_i32 s73, s72, 31
	s_ashr_i32 s75, s74, 31
	v_readlane_b32 s6, v252, 11
	s_add_u32 s0, s0, s6
	v_ashrrev_i32_e32 v5, 31, v1
	s_addc_u32 s1, s1, 0
	v_lshrrev_b32_e32 v5, 29, v5
	s_add_u32 s8, s0, 0x11400000
	v_add_u32_e32 v5, v1, v5
	s_addc_u32 s9, s1, 0
	v_lshrrev_b32_e32 v5, 3, v5
	s_add_u32 s0, s0, 0x11600000
	v_lshlrev_b32_e32 v10, 3, v1
	v_add_lshl_u32 v5, v5, v1, 4
	v_lshlrev_b32_e64 v208, v8, s7
	s_addc_u32 s1, s1, 0
	v_cmp_gt_i32_e64 s[6:7], s7, v1
	v_cmp_gt_i32_e32 vcc, 0, v1
	v_cmp_gt_i32_e64 s[4:5], s95, v1
	v_cndmask_b32_e64 v219, v4, v5, s[6:7]
	v_cndmask_b32_e64 v4, v9, v10, s[6:7]
	v_cndmask_b32_e32 v242, v2, v3, vcc
	v_cndmask_b32_e32 v2, v11, v12, vcc
	v_mov_b32_e32 v1, s1
	v_mov_b32_e32 v3, s9
	v_mov_b32_e32 v9, s0
	v_mov_b32_e32 v12, s8
	v_cndmask_b32_e64 v11, v1, v3, s[6:7]
	v_cndmask_b32_e64 v10, v9, v12, s[6:7]
	v_ashrrev_i32_e32 v5, 31, v4
	v_lshl_add_u64 v[176:177], v[4:5], 1, v[10:11]
	v_cndmask_b32_e32 v5, v1, v3, vcc
	v_cndmask_b32_e32 v4, v9, v12, vcc
	v_ashrrev_i32_e32 v3, 31, v2
	s_mov_b64 s[0:1], 0x11b0000c
	v_mul_u32_u24_e32 v171, 0x90, v202
	v_lshlrev_b32_e64 v203, v8, 1
	v_lshlrev_b32_e64 v204, v8, 2
	v_lshlrev_b32_e64 v205, v8, 4
	v_lshlrev_b32_e64 v206, v8, 8
	v_lshlrev_b32_e64 v209, v8, s95
	v_lshl_add_u64 v[178:179], v[2:3], 1, v[4:5]
	v_cndmask_b32_e64 v243, 6, 12, s[6:7]
	v_cndmask_b32_e64 v244, 6, 12, vcc
	v_lshl_add_u64 v[180:181], v[6:7], 0, s[0:1]
	v_lshlrev_b32_e32 v182, 1, v8
	s_mov_b32 s79, s86
	s_branch .LBB0_3879

; #define LAS __attribute__((address_space(3)))
; template <int DQK, int DV, int MODE, bool QNORM, int SK, int NQ> ...
;     ...
;             __builtin_amdgcn_s_setprio(1);
; #pragma unroll
;             for (int d0 = 0; d0 < DQK / 16; ++d0)
; #pragma unroll
;                 for (int sub = 0; sub < NSUB; ++sub) {
;                     const bf16x8 kf = *(const LAS bf16x8*)(sb + (sub * 32 + r32) * KP + hi * 16 + d0 * 32);
; #pragma unroll
;                     for (int qh = 0; qh < NQ; ++qh) sc[qh][sub] = __builtin_amdgcn_mfma_f32_32x32x16_bf16(kf, qf[qh][d0], sc[qh][sub], 0, 0, 0);
;                 }
;             }
;             __builtin_amdgcn_s_setprio(0);
; #pragma unroll
;             for (int sub = 0; sub < NSUB; ++sub) {
;                 const int st = NSUB * sg + sub;
;                 if (QNORM) {
; #pragma unroll
;                     for (int qh = 0; qh < NQ; ++qh)
; #pragma unroll
;                         for (int r = 0; r < 16; ++r) sc[qh][sub][r] = sc[qh][sub][r] * sscale[qh] - m_run[qh];
;                 }
;                 if (MODE == 0) {
;                     if (st * 32 + 31 > q0) {
; #pragma unroll
;                         for (int r = 0; r < 16; ++r) { if (st * 32 + crow(r, hi) > q0 + r32) {
; #pragma unroll
;                             for (int qh = 0; qh < NQ; ++qh) sc[qh][sub][r] = -INFINITY; } }
;                     }
;                 } else if (MODE == 1) {
;                     const unsigned w = sub ? wcur1 : wcur0;
; #pragma unroll
;                     for (int r = 0; r < 16; ++r) { if (((w >> crow(r, hi)) & 1u) == 0u) {
; #pragma unroll
;                         for (int qh = 0; qh < NQ; ++qh) sc[qh][sub][r] = -INFINITY; } }
;                 } else if (st >= nst_w) {
; #pragma unroll
;                     for (int qh = 0; qh < NQ; ++qh)
; #pragma unroll
;                         for (int r = 0; r < 16; ++r) sc[qh][sub][r] = -INFINITY;
;                 }
;             }
;             bf16x8 pf[NQ][NSUB][2];
; #pragma unroll
;             for (int qh = 0; qh < NQ; ++qh) {
;                 float tm = sc[qh][0][0];
; #pragma unroll
;                 for (int sub = 0; sub < NSUB; ++sub)
; #pragma unroll
;                     for (int r = 0; r < 16; ++r) tm = fmaxf(tm, sc[qh][sub][r]);
;                 tm = fmaxf(tm, __shfl_xor(tm, 32));
;                 if (__ballot(tm > 0.f) != 0ull) {
.LBB0_3901:
	s_bitcmp1_b32 s8, 0
	s_cselect_b32 s0, 0x4800, 0
	v_xor_b32_e32 v66, 0x80000000, v248
	s_add_i32 s85, s0, 0
	v_xor_b32_e32 v98, 0x80000000, v247
	v_mov_b32_e32 v67, v66
	v_mov_b32_e32 v68, v66
	v_mov_b32_e32 v69, v66
	v_mov_b32_e32 v70, v66
	v_mov_b32_e32 v71, v66
	v_mov_b32_e32 v72, v66
	v_mov_b32_e32 v73, v66
	v_mov_b32_e32 v74, v66
	v_mov_b32_e32 v75, v66
	v_mov_b32_e32 v76, v66
	v_mov_b32_e32 v77, v66
	v_mov_b32_e32 v78, v66
	v_mov_b32_e32 v79, v66
	v_mov_b32_e32 v80, v66
	v_mov_b32_e32 v81, v66
	v_mov_b32_e32 v99, v98
	v_mov_b32_e32 v100, v98
	v_mov_b32_e32 v101, v98
	v_mov_b32_e32 v102, v98
	v_mov_b32_e32 v103, v98
	v_mov_b32_e32 v104, v98
	v_mov_b32_e32 v105, v98
	v_mov_b32_e32 v106, v98
	v_mov_b32_e32 v107, v98
	v_mov_b32_e32 v108, v98
	v_mov_b32_e32 v109, v98
	v_mov_b32_e32 v110, v98
	v_mov_b32_e32 v111, v98
	v_mov_b32_e32 v112, v98
	v_mov_b32_e32 v113, v98
	s_nop 0
	v_add3_u32 v190, s85, v170, v171
	ds_read_b128 v[186:189], v190
	s_waitcnt lgkmcnt(0)
	v_mfma_f32_32x32x16_bf16 v[114:129], v[186:189], v[130:133], v[98:113]
	v_mfma_f32_32x32x16_bf16 v[82:97], v[186:189], v[146:149], v[66:81]
	ds_read_b128 v[186:189], v190 offset:4608
	s_waitcnt lgkmcnt(0)
	v_mfma_f32_32x32x16_bf16 v[98:113], v[186:189], v[130:133], v[98:113]
	v_mfma_f32_32x32x16_bf16 v[66:81], v[186:189], v[146:149], v[66:81]
	ds_read_b128 v[186:189], v190 offset:32
	s_waitcnt lgkmcnt(0)
	v_mfma_f32_32x32x16_bf16 v[114:129], v[186:189], v[134:137], v[114:129]
	v_mfma_f32_32x32x16_bf16 v[82:97], v[186:189], v[150:153], v[82:97]
	ds_read_b128 v[186:189], v190 offset:4640
	s_waitcnt lgkmcnt(0)
	v_mfma_f32_32x32x16_bf16 v[98:113], v[186:189], v[134:137], v[98:113]
	v_mfma_f32_32x32x16_bf16 v[66:81], v[186:189], v[150:153], v[66:81]
	ds_read_b128 v[186:189], v190 offset:64
	s_waitcnt lgkmcnt(0)
	v_mfma_f32_32x32x16_bf16 v[114:129], v[186:189], v[138:141], v[114:129]
	v_mfma_f32_32x32x16_bf16 v[82:97], v[186:189], v[154:157], v[82:97]
	ds_read_b128 v[186:189], v190 offset:4672
	s_waitcnt lgkmcnt(0)
	v_mfma_f32_32x32x16_bf16 v[98:113], v[186:189], v[138:141], v[98:113]
	v_mfma_f32_32x32x16_bf16 v[66:81], v[186:189], v[154:157], v[66:81]
	ds_read_b128 v[186:189], v190 offset:96
	s_waitcnt lgkmcnt(0)
	v_mfma_f32_32x32x16_bf16 v[114:129], v[186:189], v[142:145], v[114:129]
	v_mfma_f32_32x32x16_bf16 v[82:97], v[186:189], v[158:161], v[82:97]
	ds_read_b128 v[186:189], v190 offset:4704
	s_waitcnt lgkmcnt(0)
	v_mfma_f32_32x32x16_bf16 v[98:113], v[186:189], v[142:145], v[98:113]
	v_mfma_f32_32x32x16_bf16 v[66:81], v[186:189], v[158:161], v[66:81]
	s_nop 0
	s_nop 0
	v_and_b32_e32 v186, v245, v203
	v_cmp_eq_u32_e64 s[0:1], 0, v186
	v_and_b32_e32 v186, v245, v204
	v_cmp_eq_u32_e64 s[70:71], 0, v186
	v_and_b32_e32 v186, v245, v205
	v_cmp_eq_u32_e64 s[8:9], 0, v186
	v_and_b32_e32 v186, v245, v206
	v_cmp_eq_u32_e64 s[10:11], 0, v186
	v_and_b32_e32 v186, v245, v207
	v_cmp_eq_u32_e64 s[12:13], 0, v186
	v_and_b32_e32 v186, v245, v208
	v_cmp_eq_u32_e64 s[14:15], 0, v186
	v_and_b32_e32 v186, v245, v209
	v_cmp_eq_u32_e64 s[16:17], 0, v186
	v_and_b32_e32 v186, v245, v210
	v_cmp_eq_u32_e64 s[18:19], 0, v186
	v_and_b32_e32 v186, v245, v211
	v_cmp_eq_u32_e64 s[20:21], 0, v186
	v_and_b32_e32 v186, v245, v212
	v_cmp_eq_u32_e64 s[22:23], 0, v186
	v_and_b32_e32 v186, v245, v213
	v_cmp_eq_u32_e64 s[24:25], 0, v186
	v_and_b32_e32 v186, v245, v214
	v_cmp_eq_u32_e64 s[26:27], 0, v186
	v_and_b32_e32 v186, v245, v215
	v_cmp_eq_u32_e64 s[28:29], 0, v186
	v_and_b32_e32 v186, v245, v216
	v_cmp_eq_u32_e64 s[30:31], 0, v186
	v_and_b32_e32 v186, v245, v217
	v_cmp_eq_u32_e64 s[34:35], 0, v186
	v_and_b32_e32 v186, v245, v218
	v_cmp_eq_u32_e64 s[36:37], 0, v186
	v_and_b32_e32 v186, v246, v203
	v_cmp_eq_u32_e64 s[38:39], 0, v186
	v_cndmask_b32_e64 v114, v114, v238, s[0:1]
	v_cndmask_b32_e64 v115, v115, v238, s[70:71]
	v_cndmask_b32_e64 v186, v98, v238, s[38:39]
	v_and_b32_e32 v98, v246, v204
	v_cmp_eq_u32_e64 s[40:41], 0, v98
	v_and_b32_e32 v98, v246, v205
	v_cmp_eq_u32_e64 s[42:43], 0, v98
	v_and_b32_e32 v98, v246, v206
	v_cmp_eq_u32_e64 s[44:45], 0, v98
	v_and_b32_e32 v98, v246, v207
	v_cmp_eq_u32_e64 s[46:47], 0, v98
	v_and_b32_e32 v98, v246, v208
	v_cmp_eq_u32_e64 s[48:49], 0, v98
	v_and_b32_e32 v98, v246, v209
	v_cmp_eq_u32_e64 s[50:51], 0, v98
	v_and_b32_e32 v98, v246, v210
	v_cmp_eq_u32_e64 s[52:53], 0, v98
	v_and_b32_e32 v98, v246, v211
	v_cmp_eq_u32_e64 s[54:55], 0, v98
	v_and_b32_e32 v98, v246, v212
	v_cmp_eq_u32_e64 s[56:57], 0, v98
	v_and_b32_e32 v98, v246, v213
	v_cmp_eq_u32_e64 s[58:59], 0, v98
	v_and_b32_e32 v98, v246, v214
	v_cmp_eq_u32_e64 s[60:61], 0, v98
	v_and_b32_e32 v98, v246, v215
	v_cmp_eq_u32_e64 s[62:63], 0, v98
	v_and_b32_e32 v98, v246, v216
	v_cmp_eq_u32_e64 s[64:65], 0, v98
	v_and_b32_e32 v98, v246, v217
	v_cmp_eq_u32_e64 s[66:67], 0, v98
	v_and_b32_e32 v98, v246, v218
	v_cndmask_b32_e64 v187, v99, v238, s[40:41]
	v_cmp_eq_u32_e64 s[68:69], 0, v98
	v_max_f32_e32 v98, v115, v115
	v_max_f32_e32 v99, v114, v114
	v_cndmask_b32_e64 v116, v116, v238, s[8:9]
	v_cndmask_b32_e64 v117, v117, v238, s[10:11]
	v_max_f32_e32 v98, v99, v98
	v_cndmask_b32_e64 v118, v118, v238, s[12:13]
	v_cndmask_b32_e64 v119, v119, v238, s[14:15]
	v_max3_f32 v98, v98, v116, v117
	v_cndmask_b32_e64 v120, v120, v238, s[16:17]
	v_cndmask_b32_e64 v121, v121, v238, s[18:19]
	v_max3_f32 v98, v98, v118, v119
	v_cndmask_b32_e64 v122, v122, v238, s[20:21]
	v_cndmask_b32_e64 v123, v123, v238, s[22:23]
	v_max3_f32 v98, v98, v120, v121
	v_cndmask_b32_e64 v124, v124, v238, s[24:25]
	v_cndmask_b32_e64 v125, v125, v238, s[26:27]
	v_max3_f32 v98, v98, v122, v123
	v_cndmask_b32_e64 v126, v126, v238, s[28:29]
	v_cndmask_b32_e64 v127, v127, v238, s[30:31]
	v_max3_f32 v98, v98, v124, v125
	v_cndmask_b32_e64 v128, v128, v238, s[34:35]
	v_cndmask_b32_e64 v129, v129, v238, s[36:37]
	v_max3_f32 v98, v98, v126, v127
	v_max3_f32 v98, v98, v128, v129
	v_cndmask_b32_e64 v188, v100, v238, s[42:43]
	v_cndmask_b32_e64 v189, v101, v238, s[44:45]
	v_max3_f32 v98, v98, v186, v187
	v_cndmask_b32_e64 v190, v102, v238, s[46:47]
	v_cndmask_b32_e64 v191, v103, v238, s[48:49]
	v_max3_f32 v98, v98, v188, v189
	v_cndmask_b32_e64 v192, v104, v238, s[50:51]
	v_cndmask_b32_e64 v193, v105, v238, s[52:53]
	v_max3_f32 v98, v98, v190, v191
	v_cndmask_b32_e64 v194, v106, v238, s[54:55]
	v_cndmask_b32_e64 v195, v107, v238, s[56:57]
	v_max3_f32 v98, v98, v192, v193
	v_cndmask_b32_e64 v196, v108, v238, s[58:59]
	v_cndmask_b32_e64 v197, v109, v238, s[60:61]
	v_max3_f32 v98, v98, v194, v195
	v_cndmask_b32_e64 v198, v110, v238, s[62:63]
	v_cndmask_b32_e64 v199, v111, v238, s[64:65]
	v_max3_f32 v98, v98, v196, v197
	v_cndmask_b32_e64 v200, v112, v238, s[66:67]
	v_cndmask_b32_e64 v201, v113, v238, s[68:69]
	v_max3_f32 v98, v98, v198, v199
	v_max3_f32 v98, v98, v200, v201
	ds_bpermute_b32 v99, v222, v98
	s_waitcnt lgkmcnt(0)
	v_max_f32_e32 v99, v99, v99
	v_max_f32_e32 v98, v98, v99
	v_cmp_lt_f32_e32 vcc, 0, v98
	s_cbranch_vccz .LBB0_3903
; template <int DQK, int DV, int MODE, bool QNORM, int SK, int NQ> ...
;     ...
;                 if (__ballot(tm > 0.f) != 0ull) {
;                     const float dl = fmaxf(tm, 0.f); m_run[qh] += dl;
;                     const float alpha = __builtin_amdgcn_exp2f(-dl);
;                     l_run[qh] *= alpha;
; #pragma unroll
;                     for (int sub = 0; sub < NSUB; ++sub)
; #pragma unroll
;                         for (int r = 0; r < 16; ++r) sc[qh][sub][r] -= dl;
; #pragma unroll
;                     for (int dt = 0; dt < DV / 32; ++dt)
; #pragma unroll
;                         for (int r = 0; r < 16; ++r) o[qh][dt][r] *= alpha;
;                 }
	v_max_f32_e32 v98, v98, v98
	v_max_f32_e32 v98, 0, v98
	v_exp_f32_e64 v100, -v98
	v_add_f32_e32 v247, v247, v98
	v_pk_add_f32 v[114:115], v[114:115], v[98:99] op_sel_hi:[1,0] neg_lo:[0,1] neg_hi:[0,1]
	v_pk_add_f32 v[116:117], v[116:117], v[98:99] op_sel_hi:[1,0] neg_lo:[0,1] neg_hi:[0,1]
	v_mul_f32_e32 v183, v183, v100
	v_pk_add_f32 v[118:119], v[118:119], v[98:99] op_sel_hi:[1,0] neg_lo:[0,1] neg_hi:[0,1]
	v_pk_add_f32 v[120:121], v[120:121], v[98:99] op_sel_hi:[1,0] neg_lo:[0,1] neg_hi:[0,1]
	v_pk_add_f32 v[122:123], v[122:123], v[98:99] op_sel_hi:[1,0] neg_lo:[0,1] neg_hi:[0,1]
	v_pk_add_f32 v[124:125], v[124:125], v[98:99] op_sel_hi:[1,0] neg_lo:[0,1] neg_hi:[0,1]
	v_pk_add_f32 v[126:127], v[126:127], v[98:99] op_sel_hi:[1,0] neg_lo:[0,1] neg_hi:[0,1]
	v_pk_add_f32 v[128:129], v[128:129], v[98:99] op_sel_hi:[1,0] neg_lo:[0,1] neg_hi:[0,1]
	v_pk_add_f32 v[186:187], v[186:187], v[98:99] op_sel_hi:[1,0] neg_lo:[0,1] neg_hi:[0,1]
	v_pk_add_f32 v[188:189], v[188:189], v[98:99] op_sel_hi:[1,0] neg_lo:[0,1] neg_hi:[0,1]
	v_pk_add_f32 v[190:191], v[190:191], v[98:99] op_sel_hi:[1,0] neg_lo:[0,1] neg_hi:[0,1]
	v_pk_add_f32 v[192:193], v[192:193], v[98:99] op_sel_hi:[1,0] neg_lo:[0,1] neg_hi:[0,1]
	v_pk_add_f32 v[194:195], v[194:195], v[98:99] op_sel_hi:[1,0] neg_lo:[0,1] neg_hi:[0,1]
	v_pk_add_f32 v[196:197], v[196:197], v[98:99] op_sel_hi:[1,0] neg_lo:[0,1] neg_hi:[0,1]
	v_pk_add_f32 v[198:199], v[198:199], v[98:99] op_sel_hi:[1,0] neg_lo:[0,1] neg_hi:[0,1]
	v_pk_add_f32 v[200:201], v[200:201], v[98:99] op_sel_hi:[1,0] neg_lo:[0,1] neg_hi:[0,1]
	v_pk_mul_f32 v[64:65], v[64:65], v[100:101] op_sel_hi:[1,0]
	v_pk_mul_f32 v[62:63], v[62:63], v[100:101] op_sel_hi:[1,0]
	v_pk_mul_f32 v[60:61], v[60:61], v[100:101] op_sel_hi:[1,0]
	v_pk_mul_f32 v[58:59], v[58:59], v[100:101] op_sel_hi:[1,0]
	v_pk_mul_f32 v[56:57], v[56:57], v[100:101] op_sel_hi:[1,0]
	v_pk_mul_f32 v[54:55], v[54:55], v[100:101] op_sel_hi:[1,0]
	v_pk_mul_f32 v[52:53], v[52:53], v[100:101] op_sel_hi:[1,0]
	v_pk_mul_f32 v[50:51], v[50:51], v[100:101] op_sel_hi:[1,0]
	v_pk_mul_f32 v[48:49], v[48:49], v[100:101] op_sel_hi:[1,0]
	v_pk_mul_f32 v[46:47], v[46:47], v[100:101] op_sel_hi:[1,0]
	v_pk_mul_f32 v[44:45], v[44:45], v[100:101] op_sel_hi:[1,0]
	v_pk_mul_f32 v[42:43], v[42:43], v[100:101] op_sel_hi:[1,0]
	v_pk_mul_f32 v[40:41], v[40:41], v[100:101] op_sel_hi:[1,0]
	v_pk_mul_f32 v[38:39], v[38:39], v[100:101] op_sel_hi:[1,0]
	v_pk_mul_f32 v[36:37], v[36:37], v[100:101] op_sel_hi:[1,0]
	v_pk_mul_f32 v[34:35], v[34:35], v[100:101] op_sel_hi:[1,0]

; template <int DQK, int DV, int MODE, bool QNORM, int SK, int NQ> ...
;     ...
;                 float ps = 0.f;
; #pragma unroll
;                 for (int sub = 0; sub < NSUB; ++sub)
; #pragma unroll
;                     for (int r = 0; r < 16; ++r) { sc[qh][sub][r] = __builtin_amdgcn_exp2f(sc[qh][sub][r]); ps += sc[qh][sub][r]; }
;                 l_run[qh] += ps;
; #pragma unroll
;                 for (int sub = 0; sub < NSUB; ++sub) {
;                     u32x4 p0, p1;
;                     p0.x = pg8::cvt_pk_bf16(sc[qh][sub][0], sc[qh][sub][1]); p0.y = pg8::cvt_pk_bf16(sc[qh][sub][2], sc[qh][sub][3]); p0.z = pg8::cvt_pk_bf16(sc[qh][sub][4], sc[qh][sub][5]); p0.w = pg8::cvt_pk_bf16(sc[qh][sub][6], sc[qh][sub][7]);
;                     p1.x = pg8::cvt_pk_bf16(sc[qh][sub][8], sc[qh][sub][9]); p1.y = pg8::cvt_pk_bf16(sc[qh][sub][10], sc[qh][sub][11]); p1.z = pg8::cvt_pk_bf16(sc[qh][sub][12], sc[qh][sub][13]); p1.w = pg8::cvt_pk_bf16(sc[qh][sub][14], sc[qh][sub][15]);
;                     pf[qh][sub][0] = __builtin_bit_cast(bf16x8, p0); pf[qh][sub][1] = __builtin_bit_cast(bf16x8, p1);
;                 }
;             }
;             if (NQ == 1 && DQK <= 96) {
;                 bf16x8 vfa[NSUB][DV / 32][2];
; #pragma unroll
;                 for (int sub = 0; sub < NSUB; ++sub)
; #pragma unroll
;                     for (int dt = 0; dt < DV / 32; ++dt) {
;                         const LAS unsigned char* vb = sb + KBYTES + r32 * VP + (sub * 32 + hi * 8) * 2 + dt * 32 * VP;
;                         vfa[sub][dt][0] = *(const LAS bf16x8*)(vb); vfa[sub][dt][1] = *(const LAS bf16x8*)(vb + 32);
;                     }
;                 asm volatile("s_waitcnt lgkmcnt(0)" ::: "memory");
;                 __builtin_amdgcn_sched_barrier(0);
;                 __builtin_amdgcn_s_setprio(1);
; #pragma unroll
;                 for (int sub = 0; sub < NSUB; ++sub)
; #pragma unroll
;                     for (int dt = 0; dt < DV / 32; ++dt) {
;                         o[0][dt] = __builtin_amdgcn_mfma_f32_32x32x16_bf16(vfa[sub][dt][0], pf[0][sub][0], o[0][dt], 0, 0, 0);
;                         o[0][dt] = __builtin_amdgcn_mfma_f32_32x32x16_bf16(vfa[sub][dt][1], pf[0][sub][1], o[0][dt], 0, 0, 0);
;                     }
;                 __builtin_amdgcn_s_setprio(0);
;             } else {
;             __builtin_amdgcn_s_setprio(1);
; #pragma unroll
.LBB0_3905:
	v_add_f32_e32 v114, 0, v114
	v_add_f32_e32 v114, v114, v115
	v_add_f32_e32 v114, v116, v114
	v_add_f32_e32 v114, v117, v114
	v_add_f32_e32 v114, v118, v114
	v_add_f32_e32 v114, v119, v114
	v_add_f32_e32 v114, v120, v114
	v_add_f32_e32 v114, v121, v114
	v_add_f32_e32 v114, v122, v114
	v_add_f32_e32 v114, v123, v114
	v_add_f32_e32 v114, v124, v114
	v_add_f32_e32 v114, v125, v114
	v_add_f32_e32 v114, v126, v114
	v_add_f32_e32 v114, v127, v114
	v_add_f32_e32 v114, v128, v114
	v_add_f32_e32 v114, v129, v114
	v_add_f32_e32 v114, v186, v114
	v_add_f32_e32 v114, v187, v114
	v_add_f32_e32 v114, v188, v114
	v_add_f32_e32 v114, v189, v114
	v_add_f32_e32 v114, v190, v114
	v_add_f32_e32 v114, v191, v114
	v_add_f32_e32 v114, v192, v114
	v_add_f32_e32 v114, v193, v114
	v_add_f32_e32 v114, v194, v114
	v_add_f32_e32 v114, v195, v114
	v_add_f32_e32 v114, v196, v114
	v_add_f32_e32 v114, v197, v114
	v_add_f32_e32 v114, v198, v114
	v_exp_f32_e32 v112, v112
	v_add_f32_e32 v114, v199, v114
	v_exp_f32_e32 v113, v113
	v_add_f32_e32 v114, v200, v114
	v_exp_f32_e32 v110, v110
	v_add_f32_e32 v114, v201, v114
	v_exp_f32_e32 v111, v111
	v_add_f32_e32 v183, v183, v114
	v_add_f32_e32 v114, 0, v112
	v_exp_f32_e32 v108, v108
	v_add_f32_e32 v114, v114, v113
	v_exp_f32_e32 v109, v109
	v_add_f32_e32 v114, v110, v114
	v_exp_f32_e32 v106, v106
	v_add_f32_e32 v114, v111, v114
	v_exp_f32_e32 v107, v107
	v_add_f32_e32 v114, v108, v114
	v_exp_f32_e32 v104, v104
	v_add_f32_e32 v114, v109, v114
	v_exp_f32_e32 v105, v105
	v_add_f32_e32 v114, v106, v114
	v_exp_f32_e32 v102, v102
	v_add_f32_e32 v114, v107, v114
	v_exp_f32_e32 v103, v103
	v_add_f32_e32 v114, v104, v114
	v_exp_f32_e32 v100, v100
	v_add_f32_e32 v114, v105, v114
	v_exp_f32_e32 v101, v101
	v_add_f32_e32 v114, v102, v114
	v_exp_f32_e32 v98, v98
	v_add_f32_e32 v114, v103, v114
	v_exp_f32_e32 v99, v99
	v_add_f32_e32 v114, v100, v114
	v_exp_f32_e32 v96, v96
	v_add_f32_e32 v114, v101, v114
	v_exp_f32_e32 v97, v97
	v_add_f32_e32 v114, v98, v114
	v_exp_f32_e32 v94, v94
	v_add_f32_e32 v114, v99, v114
	v_exp_f32_e32 v95, v95
	v_add_f32_e32 v114, v96, v114
	v_exp_f32_e32 v92, v92
	v_add_f32_e32 v114, v97, v114
	v_exp_f32_e32 v93, v93
	v_add_f32_e32 v114, v94, v114
	v_exp_f32_e32 v115, v90
	v_add_f32_e32 v114, v95, v114
	v_exp_f32_e32 v116, v91
	v_add_f32_e32 v90, v92, v114
	v_exp_f32_e32 v114, v88
	v_add_f32_e32 v90, v93, v90
	v_exp_f32_e32 v117, v89
	v_add_f32_e32 v90, v115, v90
	v_exp_f32_e32 v118, v86
	v_add_f32_e32 v90, v116, v90
	v_exp_f32_e32 v119, v87
	v_add_f32_e32 v86, v114, v90
	v_exp_f32_e32 v120, v84
	v_add_f32_e32 v86, v117, v86
	v_exp_f32_e32 v121, v85
	v_add_f32_e32 v86, v118, v86
	v_exp_f32_e32 v122, v82
	v_add_f32_e32 v86, v119, v86
	v_exp_f32_e32 v123, v83
	v_add_f32_e32 v82, v120, v86
	v_add_f32_e32 v82, v121, v82
	v_add_f32_e32 v82, v122, v82
	v_add_f32_e32 v82, v123, v82
	v_readlane_b32 s68, v252, 27
	v_add_f32_e32 v1, v1, v82
	v_readlane_b32 s69, v252, 28
	v_readlane_b32 s70, v252, 29
	v_readlane_b32 s71, v252, 30
	v_cvt_pk_bf16_f32 v82, v112, v113
	v_cvt_pk_bf16_f32 v83, v110, v111
	v_cvt_pk_bf16_f32 v84, v108, v109
	v_cvt_pk_bf16_f32 v85, v106, v107
	v_cvt_pk_bf16_f32 v86, v104, v105
	v_cvt_pk_bf16_f32 v87, v102, v103
	v_cvt_pk_bf16_f32 v88, v100, v101
	v_cvt_pk_bf16_f32 v89, v98, v99
	v_cvt_pk_bf16_f32 v90, v96, v97
	v_cvt_pk_bf16_f32 v91, v94, v95
	v_cvt_pk_bf16_f32 v92, v92, v93
	v_cvt_pk_bf16_f32 v93, v115, v116
	v_cvt_pk_bf16_f32 v94, v114, v117
	v_cvt_pk_bf16_f32 v95, v118, v119
	v_cvt_pk_bf16_f32 v96, v120, v121
	v_cvt_pk_bf16_f32 v97, v122, v123
	s_nop 0
	v_add3_u32 v106, s85, v171, v170
	ds_read_b128 v[98:101], v106 offset:9216
	ds_read_b128 v[102:105], v106 offset:9248
	s_waitcnt lgkmcnt(1)
	v_mfma_f32_32x32x16_bf16 v[50:65], v[98:101], v[70:73], v[50:65]
	v_mfma_f32_32x32x16_bf16 v[18:33], v[98:101], v[82:85], v[18:33]
	s_waitcnt lgkmcnt(0)
	v_mfma_f32_32x32x16_bf16 v[50:65], v[102:105], v[74:77], v[50:65]
	v_mfma_f32_32x32x16_bf16 v[18:33], v[102:105], v[86:89], v[18:33]
	ds_read_b128 v[98:101], v106 offset:13824
	ds_read_b128 v[102:105], v106 offset:13856
	s_waitcnt lgkmcnt(1)
	v_mfma_f32_32x32x16_bf16 v[34:49], v[98:101], v[70:73], v[34:49]
	s_waitcnt lgkmcnt(0)
	v_mfma_f32_32x32x16_bf16 v[34:49], v[102:105], v[74:77], v[34:49]
	ds_read_b128 v[70:73], v106 offset:9280
	ds_read_b128 v[74:77], v106 offset:9312
	v_mfma_f32_32x32x16_bf16 v[2:17], v[98:101], v[82:85], v[2:17]
	s_waitcnt lgkmcnt(1)
	v_mfma_f32_32x32x16_bf16 v[50:65], v[70:73], v[66:69], v[50:65]
	v_mfma_f32_32x32x16_bf16 v[18:33], v[70:73], v[90:93], v[18:33]
	v_mfma_f32_32x32x16_bf16 v[2:17], v[102:105], v[86:89], v[2:17]
	s_waitcnt lgkmcnt(0)
	v_mfma_f32_32x32x16_bf16 v[50:65], v[74:77], v[78:81], v[50:65]
	v_mfma_f32_32x32x16_bf16 v[18:33], v[74:77], v[94:97], v[18:33]
	ds_read_b128 v[70:73], v106 offset:13888
	ds_read_b128 v[74:77], v106 offset:13920
	s_waitcnt lgkmcnt(1)
	v_mfma_f32_32x32x16_bf16 v[34:49], v[70:73], v[66:69], v[34:49]
	v_mfma_f32_32x32x16_bf16 v[2:17], v[70:73], v[90:93], v[2:17]
	s_waitcnt lgkmcnt(0)
	v_mfma_f32_32x32x16_bf16 v[34:49], v[74:77], v[78:81], v[34:49]
	v_mfma_f32_32x32x16_bf16 v[2:17], v[74:77], v[94:97], v[2:17]
	s_nop 0
	s_andn2_b64 vcc, exec, s[76:77]
	s_cbranch_vccnz .LBB0_3911

; __device__ __forceinline__ unsigned xb_add(unsigned* p, unsigned v) { return __hip_atomic_fetch_add(p, v, __ATOMIC_RELAXED, __HIP_MEMORY_SCOPE_AGENT); }
; __device__ __forceinline__ void xcd_barrier(const XcdBarrier& b) {
;     asm volatile("s_waitcnt vmcnt(0)" ::: "memory");
;     __syncthreads();
;     if (b.tid == 0u) {
;         unsigned* bar = b.bar;
;         __builtin_amdgcn_s_waitcnt(0);
;         unsigned nloc = b.st[0], nx = b.st[1];
;         if (nloc == 0u) { xcd_barrier_complete(bar, b.x, nloc, nx); b.st[0] = nloc; b.st[1] = nx; }
;         const unsigned old = xb_add(&bar[XB_XSUB(b.x)], 1u);
; __global__ void __launch_bounds__(512, 2) mega_fwd(KArgs a) {
;     ...
;             GSYNC();
.LBB0_3913:
	s_mov_b64 s[2:3], s[88:89]
	s_getreg_b32 s4, hwreg(HW_REG_XCC_ID, 0, 4)
	s_waitcnt vmcnt(0)
	s_setprio 0
	s_barrier
	s_mov_b64 s[0:1], exec
	v_readlane_b32 s6, v252, 2
	v_readlane_b32 s7, v252, 3
	s_and_b64 s[6:7], s[0:1], s[6:7]
	s_mov_b32 s72, 0x2aaaaaab
	s_movk_i32 s73, 0x300
	s_mov_b32 s81, 0x8c05000
	s_mov_b64 exec, s[6:7]
	s_cbranch_execz .LBB0_3965
	v_readlane_b32 s5, v252, 13
	s_load_dwordx2 s[2:3], s[2:3], 0x100
	s_waitcnt vmcnt(0) expcnt(0) lgkmcnt(0)
	v_mov_b32_e32 v1, s5
	ds_read_b32 v3, v1
	v_readlane_b32 s5, v252, 14
	s_and_b32 s46, s4, 15
	s_waitcnt lgkmcnt(0)
	v_cmp_ne_u32_e32 vcc, 0, v3
	v_mov_b32_e32 v1, s5
	ds_read_b32 v2, v1
	s_cbranch_vccnz .LBB0_3929
	s_add_u32 s4, s2, 0x17900200
	s_addc_u32 s5, s3, 0
	s_add_u32 s6, s2, 0x17900400
	s_addc_u32 s7, s3, 0
	s_add_u32 s8, s2, 0x17900500
	s_addc_u32 s9, s3, 0
	s_add_u32 s10, s2, 0x17900600
	s_addc_u32 s11, s3, 0
	s_add_u32 s12, s2, 0x17900700
	s_addc_u32 s13, s3, 0
	s_add_u32 s14, s2, 0x17900800
	s_addc_u32 s15, s3, 0
	s_add_u32 s16, s2, 0x17900900
	s_addc_u32 s17, s3, 0
	s_add_u32 s18, s2, 0x17900a00
	s_addc_u32 s19, s3, 0
	s_add_u32 s20, s2, 0x17900b00
	s_addc_u32 s21, s3, 0
	s_add_u32 s22, s2, 0x17900c00
	s_addc_u32 s23, s3, 0
	s_add_u32 s24, s2, 0x17900d00
	s_addc_u32 s25, s3, 0
	s_add_u32 s26, s2, 0x17900e00
	s_addc_u32 s27, s3, 0
	s_add_u32 s28, s2, 0x17900f00
	s_addc_u32 s29, s3, 0
	s_add_u32 s30, s2, 0x17901000
	s_addc_u32 s31, s3, 0
	s_add_u32 s34, s2, 0x17901100
	s_addc_u32 s35, s3, 0
	s_add_u32 s36, s2, 0x17901200
	s_addc_u32 s37, s3, 0
	s_add_u32 s38, s2, 0x17901300
	s_addc_u32 s39, s3, 0
	s_mov_b32 s47, 1
	s_branch .LBB0_3917
